# static priority raise for the older half (waves 0-3) instead, all per-segment flips deleted
# speedup vs baseline: 1.0062x; 1.0022x over previous
_Z3fwd4Args:
	v_readfirstlane_b32 s98, v0
	s_nop 3
	s_and_b32 s98, s98, 0x3ff
	s_lshr_b32 s98, s98, 6
	s_cmp_lt_u32 s98, 4
	s_cbranch_scc0 .Lprio_done
	s_setprio 1
